# O1 drop tile-top vmcnt0, O2 hoist ktile1 prologue loads, G5 epilogue fast path, MLA prio waves4-7, within-XCD stagger steps 1/6/7
# baseline (speedup 1.0000x reference)
; #define opqp(x) ((x) + opqz())
; __device__ void gemm_step(const P& p, int step, int l) {
;   OPQ_IDS
;   char* ws = opqp(p.ws);
;   const int nM = NTOK / 256;
;   const bool need_ctx = l < 3;
;   int ntiles;
;   const int nbr = 1;
;   if (step == 1) ntiles = nM * (NP / BNT);
;   else if (step == 3) ntiles = nM * (2304 / BNT);
;   else if (step == 6) ntiles = 4 * nM * (2048 / BNT);
;   else if (step == 7) ntiles = nM * 32;
;   else ntiles = nM * (2048 / BNT);
;   for (int t0 = BIDX; t0 < (ntiles + 255) / 256 * 256; t0 += gridDim.x) {
;     const int t = xcd_remap(t0, BIDX, gridDim.x);
;     if (t >= ntiles) continue;
.LBB0_160:
	s_add_i32 s4, s86, 0xff
	s_and_b32 s87, s4, 0x1f00
	s_cmp_ge_i32 s74, s87
	s_cbranch_scc1 .LBB0_319
	v_writelane_b32 v249, s50, 62
	s_nop 1
	v_writelane_b32 v249, s51, 63
	s_nop 0
	v_readlane_b32 s4, v249, 42
	v_readlane_b32 s8, v249, 46
	v_readlane_b32 s9, v249, 47
	s_add_u32 s48, s8, s2
	s_addc_u32 s49, s9, s3
	s_cmp_gt_u32 s77, 53
	s_cselect_b64 s[2:3], -1, 0
	s_lshl_b32 s4, s74, 5
	s_and_b32 s96, s4, 0xe0
	s_ashr_i32 s4, s74, 3
	s_add_i32 s96, s96, s4
	v_readlane_b32 s5, v249, 43
	s_add_u32 s52, s48, 0x5e8a000
	s_addc_u32 s53, s49, 0
	v_readlane_b32 s5, v249, 55
	s_bitcmp0_b32 s5, 0
	s_mov_b32 s4, 0x1c50000
	v_readlane_b32 s6, v249, 44
	s_cselect_b32 s4, s4, 0x37862600
	v_readlane_b32 s7, v249, 45
	s_add_u32 s6, s48, s4
	s_addc_u32 s7, s49, 0
	v_writelane_b32 v248, s6, 0
	s_add_u32 s4, s48, 0x2223c000
	s_addc_u32 s75, s49, 0
	v_writelane_b32 v248, s7, 1
	v_writelane_b32 v248, s4, 2
	s_add_u32 s4, s48, 0x3c50000
	v_writelane_b32 v248, s4, 3
	s_addc_u32 s4, s49, 0
	s_add_u32 s6, s48, 0xa28b800
	v_writelane_b32 v248, s4, 5
	s_addc_u32 s7, s49, 0
	v_writelane_b32 v248, s6, 7
	v_readlane_b32 s10, v249, 48
	v_readlane_b32 s11, v249, 49
	v_writelane_b32 v248, s7, 8
	s_add_u32 s6, s48, 0x4c50000
	s_addc_u32 s7, s49, 0
	v_writelane_b32 v248, s6, 9
	s_nop 1
	v_writelane_b32 v248, s7, 10
	s_add_u32 s6, s48, 0x2663c000
	s_addc_u32 s7, s49, 0
	v_writelane_b32 v248, s6, 11
	s_nop 1
	v_writelane_b32 v248, s7, 12
	s_add_u32 s6, s48, 0x4450000
	s_addc_u32 s7, s49, 0
	v_writelane_b32 v248, s6, 13
	s_and_b64 s[24:25], s[2:3], s[28:29]
	s_lshl_b32 s2, s5, 9
	v_writelane_b32 v248, s7, 14
	s_cmp_lt_u32 s77, 18
	v_writelane_b32 v248, s2, 15
	s_cselect_b64 s[42:43], -1, 0
	s_and_b32 s2, 0xffff, s5
	s_mul_i32 s3, s2, 5
	v_writelane_b32 v248, s3, 16
	s_mul_i32 s2, s2, 0x1e000
	v_writelane_b32 v248, s2, 17
	s_and_b64 s[2:3], s[38:39], exec
	s_mov_b32 s2, 0x1dd0a000
	s_cselect_b32 s2, s2, 0x1cc0a000
	s_add_u32 s2, s8, s2
	s_addc_u32 s3, s9, 0
	v_writelane_b32 v248, s2, 18
	s_nop 1
	v_writelane_b32 v248, s3, 19
	v_readlane_b32 s4, v249, 56
	s_lshr_b32 s3, s26, 3
	s_and_b32 s3, s3, 3
	s_nop 1
	s_cmp_eq_u32 s4, 1
	s_cselect_b32 s5, 1, 0
	s_cmp_eq_u32 s4, 6
	s_cselect_b32 s5, 1, s5
	s_cmp_eq_u32 s4, 7
	s_cselect_b32 s5, 1, s5
	s_mul_i32 s3, s3, s5
	s_cmp_eq_u32 s3, 0
	s_cbranch_scc1 .Lstag_done
.Lstag_loop:
	s_sleep 60
	s_add_i32 s3, s3, -1
	s_cmp_lg_u32 s3, 0
	s_cbranch_scc1 .Lstag_loop

; #define WAIT_V(n) asm volatile("s_waitcnt vmcnt(" #n ")" ::: "memory")
; #define BAR __builtin_amdgcn_s_barrier()
; DEVI void gemm256(const P& p, const u16* A, int lda, const u16* Bt, int ldb, int K, int brow, int bcol, int mode,
;                         int aux, int layer, int bmode) {
;     ...
;   STAGEB(SB(0, 0), bcol, 0);
;   STAGEA(SA(0, 0), brow, 0);
;   STAGEB(SB(0, 1), bcol + bhalf, 0);
;   STAGEA(SA(0, 1), brow + HALF, 0);
;   if (wr == 1) BAR;
;   WAIT_V(4);
;   BAR;
;   STAGEB(SB(1, 0), bcol, 1);
;   STAGEA(SA(1, 0), brow, 1);
;   STAGEB(SB(1, 1), bcol + bhalf, 1);
.LBB0_189:
	s_lshl_b32 s70, s4, 8
	s_mul_i32 s97, s7, s6
	s_and_b64 s[2:3], s[46:47], exec
	s_movk_i32 s2, 0x80
	s_mul_i32 s3, s97, s5
	s_cselect_b32 s2, s2, 0x1000
	s_lshl_b32 s6, s3, 1
	v_readlane_b32 s3, v249, 20
	s_add_i32 s2, s97, s2
	s_and_b32 s29, s29, 0xffff
	v_add_u32_e32 v145, s3, v0
	v_add_u32_e32 v146, 0x2000, v145
	v_readfirstlane_b32 s3, v145
	s_mov_b32 m0, s3
	v_readfirstlane_b32 s3, v146
	v_add_u32_e32 v147, 16, v0
	s_mul_i32 s2, s2, s5
	v_mul_lo_u32 v2, v2, s9
	buffer_load_dwordx4 v136, s[28:31], s6 offen lds
	s_mov_b32 m0, s3
	s_mul_i32 s7, s9, s70
	v_readfirstlane_b32 s3, v147
	v_add_u32_e32 v148, 0x2000, v147
	s_lshl_b32 s8, s2, 1
	v_readlane_b32 s2, v249, 21
	s_and_b32 s45, s45, 0xffff
	s_mov_b32 s46, s30
	s_mov_b32 s47, s31
	v_add_lshl_u32 v143, v3, v2, 1
	v_mul_lo_u32 v2, v4, s9
	buffer_load_dwordx4 v137, s[28:31], s6 offen lds
	s_lshl_b32 s10, s7, 1
	s_mov_b32 m0, s3
	v_readfirstlane_b32 s3, v148
	v_add_u32_e32 v150, s2, v0
	v_add_lshl_u32 v142, v5, v2, 1
	buffer_load_dwordx4 v143, s[44:47], s10 offen lds
	s_mov_b32 m0, s3
	v_readfirstlane_b32 s2, v150
	v_add_u32_e32 v151, 0x2000, v150
	buffer_load_dwordx4 v142, s[44:47], s10 offen lds
	s_mov_b32 m0, s2
	v_readfirstlane_b32 s2, v151
	buffer_load_dwordx4 v136, s[28:31], s8 offen lds
	s_mov_b32 m0, s2
	s_lshl_b32 s2, s9, 7
	v_add_u32_e32 v152, 0x4000, v147
	s_add_i32 s7, s7, s2
	v_readfirstlane_b32 s3, v152
	v_add_u32_e32 v153, 0x6000, v147
	buffer_load_dwordx4 v137, s[28:31], s8 offen lds
	s_lshl_b32 s2, s7, 1
	s_mov_b32 m0, s3
	v_readfirstlane_b32 s3, v153
	buffer_load_dwordx4 v143, s[44:47], s2 offen lds
	s_mov_b32 m0, s3
	v_ashrrev_i32_e32 v132, 8, v130
	buffer_load_dwordx4 v142, s[44:47], s2 offen lds
	v_readlane_b32 s12, v249, 22
	s_or_b32 s3, s6, 0x80
	s_nop 1
	v_add_u32_e32 v154, s12, v0
	v_add_u32_e32 v155, 0x2000, v154
	v_readfirstlane_b32 s11, v154
	s_mov_b32 m0, s11
	v_readfirstlane_b32 s11, v155
	buffer_load_dwordx4 v136, s[28:31], s3 offen lds
	s_mov_b32 m0, s11
	v_add_u32_e32 v156, 0x8000, v147
	buffer_load_dwordx4 v137, s[28:31], s3 offen lds
	v_readfirstlane_b32 s3, v156
	v_add_u32_e32 v157, 0xa000, v147
	s_bitset1_b32 s10, 7
	s_mov_b32 s46, s30
	s_mov_b32 s47, s31
	s_mov_b32 m0, s3
	v_readfirstlane_b32 s3, v157
	v_readlane_b32 s11, v249, 23
	buffer_load_dwordx4 v143, s[44:47], s10 offen lds
	s_mov_b32 m0, s3
	v_add_u32_e32 v161, s11, v0
	buffer_load_dwordx4 v142, s[44:47], s10 offen lds
	v_readfirstlane_b32 s10, v161
	v_add_u32_e32 v162, 0x2000, v161
	s_or_b32 s3, s8, 0x80
	s_mov_b32 m0, s10
	v_readfirstlane_b32 s10, v162
	buffer_load_dwordx4 v136, s[28:31], s3 offen lds
	s_mov_b32 m0, s10
	v_and_b32_e32 v131, 15, v130
	buffer_load_dwordx4 v137, s[28:31], s3 offen lds
	v_cmp_eq_u32_e32 vcc, 1, v132
	s_and_saveexec_b64 s[2:3], vcc
	s_cbranch_execz .LBB0_191
	s_barrier
; #define WAIT_V(n) asm volatile("s_waitcnt vmcnt(" #n ")" ::: "memory")
; #define BAR __builtin_amdgcn_s_barrier()
; DEVI void gemm256(const P& p, const u16* A, int lda, const u16* Bt, int ldb, int K, int brow, int bcol, int mode,
;                         int aux, int layer, int bmode) {
;     ...
;   if (wr == 1) BAR;
;   WAIT_V(4);
;   BAR;
;   STAGEB(SB(1, 0), bcol, 1);
;   STAGEA(SA(1, 0), brow, 1);
;   STAGEB(SB(1, 1), bcol + bhalf, 1);
;   WAIT_V(6);
;   BAR;
;   for (int t = 0; t < nt - 2; t += 2) {
.LBB0_191:
	s_or_b64 exec, exec, s[2:3]
	s_waitcnt vmcnt(10)
	s_barrier
	v_bfe_u32 v134, v130, 4, 2
	v_lshlrev_b32_e32 v4, 2, v130
	v_lshlrev_b32_e32 v2, 4, v134
	v_lshlrev_b32_e32 v3, 6, v131
	v_and_b32_e32 v4, 32, v4
	v_bitop3_b32 v3, v2, v4, v3 bitop3:0x36
	v_readlane_b32 s3, v249, 20
	v_lshrrev_b32_e32 v133, 4, v130
	s_waitcnt vmcnt(27)
	v_lshlrev_b32_e32 v11, 6, v130
	v_add_u32_e32 v5, s3, v3
	v_readlane_b32 s3, v249, 21
	s_waitcnt vmcnt(6)
	v_and_b32_e32 v135, 12, v133
	v_lshlrev_b32_e32 v10, 13, v132
	v_add_u32_e32 v6, s3, v3
	s_movk_i32 s3, 0x3c0
	v_and_or_b32 v2, v11, s3, v2
	s_add_i32 s3, s70, 0x80
	s_lshr_b32 s2, s5, 6
	v_add_u32_e32 v7, s12, v3
	v_add_u32_e32 v8, s11, v3
	v_lshlrev_b32_e32 v9, 10, v135
	v_add_u32_e32 v3, 16, v3
	v_xad_u32 v4, v2, v4, 16
	v_or_b32_e32 v11, 0x800, v10
	v_or_b32_e32 v12, 0x1000, v10
	v_or_b32_e32 v13, 0x1800, v10
	s_mul_i32 s3, s9, s3
	s_lshl_b32 s4, s4, 9
	v_mov_b32_e32 v2, 0
	s_xor_b64 s[36:37], s[36:37], -1
	s_xor_b64 s[78:79], s[54:55], -1
	s_add_i32 s2, s2, -2
	v_add_u32_e32 v159, 0xc000, v147
	v_add_u32_e32 v158, 0xe000, v147
	s_lshl_b32 s3, s3, 1
	s_mul_i32 s9, s4, s9
	s_mov_b32 s10, 0
	v_add_u32_e32 v163, v5, v9
	v_add_u32_e32 v141, v3, v10
	v_add_u32_e32 v140, v4, v11
	v_add_u32_e32 v139, v4, v12
	v_add_u32_e32 v138, v4, v13
	v_add_u32_e32 v160, v6, v9
	v_add_u32_e32 v149, v7, v9
	v_add_u32_e32 v144, v8, v9
	s_mov_b32 s11, 0
	v_mov_b32_e32 v3, v2
	v_mov_b32_e32 v4, v2
	v_mov_b32_e32 v5, v2
	v_mov_b32_e32 v6, v2
	v_mov_b32_e32 v7, v2
	v_mov_b32_e32 v8, v2
	v_mov_b32_e32 v9, v2
	v_mov_b32_e32 v10, v2
	v_mov_b32_e32 v11, v2
	v_mov_b32_e32 v12, v2
	v_mov_b32_e32 v13, v2
	s_waitcnt vmcnt(26)
	v_mov_b32_e32 v14, v2
	v_mov_b32_e32 v15, v2
	v_mov_b32_e32 v16, v2
	v_mov_b32_e32 v17, v2
	s_waitcnt vmcnt(25)
	v_mov_b32_e32 v18, v2
	v_mov_b32_e32 v19, v2
	v_mov_b32_e32 v20, v2
	v_mov_b32_e32 v21, v2
	s_waitcnt vmcnt(24)
	v_mov_b32_e32 v22, v2
	v_mov_b32_e32 v23, v2
	v_mov_b32_e32 v24, v2
	v_mov_b32_e32 v25, v2
	s_waitcnt vmcnt(23)
	v_mov_b32_e32 v26, v2
	v_mov_b32_e32 v27, v2
	v_mov_b32_e32 v28, v2
	v_mov_b32_e32 v29, v2
	s_waitcnt vmcnt(22)
	v_mov_b32_e32 v30, v2
	v_mov_b32_e32 v31, v2
	v_mov_b32_e32 v32, v2
	v_mov_b32_e32 v33, v2
	s_waitcnt vmcnt(14)
	v_mov_b32_e32 v62, v2
	v_mov_b32_e32 v63, v2
	v_mov_b32_e32 v64, v2
	v_mov_b32_e32 v65, v2
	v_mov_b32_e32 v82, v2
	v_mov_b32_e32 v83, v2
	v_mov_b32_e32 v84, v2
	v_mov_b32_e32 v85, v2
	v_mov_b32_e32 v98, v2
	v_mov_b32_e32 v99, v2
	v_mov_b32_e32 v100, v2
	v_mov_b32_e32 v101, v2
	v_mov_b32_e32 v110, v2
	v_mov_b32_e32 v111, v2
	v_mov_b32_e32 v112, v2
	v_mov_b32_e32 v113, v2
	v_mov_b32_e32 v114, v2
	v_mov_b32_e32 v115, v2
	v_mov_b32_e32 v116, v2
	v_mov_b32_e32 v117, v2
	v_mov_b32_e32 v118, v2
	v_mov_b32_e32 v119, v2
	v_mov_b32_e32 v120, v2
	v_mov_b32_e32 v121, v2
	v_mov_b32_e32 v122, v2
	v_mov_b32_e32 v123, v2
	v_mov_b32_e32 v124, v2
	v_mov_b32_e32 v125, v2
	v_mov_b32_e32 v126, v2
	v_mov_b32_e32 v127, v2
	v_mov_b32_e32 v128, v2
	v_mov_b32_e32 v129, v2
	v_mov_b32_e32 v34, v2
	v_mov_b32_e32 v35, v2
	v_mov_b32_e32 v36, v2
	v_mov_b32_e32 v37, v2
	v_mov_b32_e32 v38, v2
	v_mov_b32_e32 v39, v2
	v_mov_b32_e32 v40, v2
	v_mov_b32_e32 v41, v2
	v_mov_b32_e32 v42, v2
	v_mov_b32_e32 v43, v2
	v_mov_b32_e32 v44, v2
	v_mov_b32_e32 v45, v2
	v_mov_b32_e32 v46, v2
	v_mov_b32_e32 v47, v2
	v_mov_b32_e32 v48, v2
	v_mov_b32_e32 v49, v2
	v_mov_b32_e32 v50, v2
	v_mov_b32_e32 v51, v2
	v_mov_b32_e32 v52, v2
	v_mov_b32_e32 v53, v2
	v_mov_b32_e32 v54, v2
	v_mov_b32_e32 v55, v2
	v_mov_b32_e32 v56, v2
	v_mov_b32_e32 v57, v2
	v_mov_b32_e32 v58, v2
	v_mov_b32_e32 v59, v2
	v_mov_b32_e32 v60, v2
	v_mov_b32_e32 v61, v2
	v_mov_b32_e32 v70, v2
	v_mov_b32_e32 v71, v2
	v_mov_b32_e32 v72, v2
	v_mov_b32_e32 v73, v2
	v_mov_b32_e32 v66, v2
	v_mov_b32_e32 v67, v2
	v_mov_b32_e32 v68, v2
	v_mov_b32_e32 v69, v2
	v_mov_b32_e32 v74, v2
	v_mov_b32_e32 v75, v2
	v_mov_b32_e32 v76, v2
	v_mov_b32_e32 v77, v2
	v_mov_b32_e32 v78, v2
	v_mov_b32_e32 v79, v2
	v_mov_b32_e32 v80, v2
	v_mov_b32_e32 v81, v2
	v_mov_b32_e32 v86, v2
	v_mov_b32_e32 v87, v2
	v_mov_b32_e32 v88, v2
	v_mov_b32_e32 v89, v2
	v_mov_b32_e32 v90, v2
	v_mov_b32_e32 v91, v2
	v_mov_b32_e32 v92, v2
	v_mov_b32_e32 v93, v2
	v_mov_b32_e32 v94, v2
	v_mov_b32_e32 v95, v2
	v_mov_b32_e32 v96, v2
	v_mov_b32_e32 v97, v2
	v_mov_b32_e32 v102, v2
	v_mov_b32_e32 v103, v2
	v_mov_b32_e32 v104, v2
	v_mov_b32_e32 v105, v2
	v_mov_b32_e32 v106, v2
	v_mov_b32_e32 v107, v2
	v_mov_b32_e32 v108, v2
	v_mov_b32_e32 v109, v2
	s_barrier

; DEVI float bfs(short h) { return __uint_as_float(((unsigned)(u16)h) << 16); }
; template <int DQK, int QT, bool NA> ...
;     ...
;     if (!NA && DQK == 192) {
; #pragma unroll
;       for (int qt = 0; qt < QT; ++qt) {
;         const int ql = wid * 16 * QT + qt * 16 + l15;
;         const u16* qp = Qbase + (size_t)(qrow0 + ql) * ldq;
;         const int tq = (qrow0 + ql) % TPB - CTXL;
; #pragma unroll
;         for (int hf = 0; hf < 2; ++hf) {
;           bf16x8 own = qf[qt][KS - 2 + hf];
;           bf16x8 par = *(const bf16x8*)(qp + 128 + hf * 32 + (quad ^ 2) * 8);
;           int pp = hf ? (tq & 63) : (tq >> 6);
;           bf16x8 ro;
; #pragma unroll
;           for (int e = 0; e < 8; ++e) {
;             float2 cs = rt[pp * 16 + (quad & 1) * 8 + e];
;             float ov = bfs(own[e]), pv = bfs(par[e]);
;             float r = (quad < 2) ? ov * cs.x - pv * cs.y : ov * cs.x + pv * cs.y;
;             ro[e] = (short)f2bf(r);
;           }
;           qf[qt][KS - 2 + hf] = ro;
;         }
;       }
.LBB0_786:
	s_mov_b32 s2, 0x78787879
	v_mul_hi_i32 v136, v162, s2
	v_xor_b32_e32 v0, 16, v212
	v_lshrrev_b32_e32 v137, 31, v136
	v_ashrrev_i32_e32 v136, 11, v136
	v_lshl_add_u64 v[2:3], s[34:35], 0, v[152:153]
	v_add_u32_e32 v140, v136, v137
	v_lshlrev_b32_e32 v0, 1, v0
	v_lshl_add_u64 v[156:157], v[2:3], 0, v[0:1]
	v_mul_i32_i24_e32 v2, 0x1100, v140
	v_sub_u32_e32 v181, v162, v2
	s_add_u32 s0, s72, s0
	v_add_u32_e32 v2, 0xffffff00, v181
	s_addc_u32 s1, s73, s1
	v_and_b32_e32 v180, 8, v212
	v_ashrrev_i32_e32 v2, 2, v2
	s_add_u32 s36, s0, 0x5688000
	v_and_or_b32 v2, v2, -16, v180
	s_addc_u32 s37, s1, 0
	v_ashrrev_i32_e32 v3, 31, v2
	global_load_dwordx4 v[136:139], v[156:157], off offset:256
	v_lshl_add_u64 v[2:3], v[2:3], 3, s[36:37]
	global_load_dwordx4 v[152:155], v[2:3], off
	global_load_dwordx4 v[148:151], v[2:3], off offset:16
	global_load_dwordx4 v[144:147], v[2:3], off offset:32
	global_load_dwordx4 v[140:143], v[2:3], off offset:48
	v_and_b32_e32 v3, 0xffff0000, v132
	v_lshlrev_b32_e32 v2, 16, v132
	v_lshlrev_b32_e32 v132, 4, v181
	s_movk_i32 s3, 0x3f0
	v_and_or_b32 v132, v132, s3, v180
	v_lshlrev_b32_e32 v181, 3, v132
	global_load_dwordx4 v[156:159], v[156:157], off offset:320
	v_and_b32_e32 v225, 0xffff0000, v134
	global_load_dwordx4 v[212:215], v181, s[36:37]
	v_lshlrev_b32_e32 v224, 16, v134
	v_mul_hi_i32 v134, v160, s2
	v_and_b32_e32 v227, 0xffff0000, v135
	v_lshlrev_b32_e32 v226, 16, v135
	v_lshrrev_b32_e32 v135, 31, v134
	v_ashrrev_i32_e32 v134, 11, v134
	v_and_b32_e32 v179, 0xffff0000, v133
	v_lshlrev_b32_e32 v178, 16, v133
	v_lshl_add_u64 v[132:133], s[34:35], 0, v[176:177]
	v_add_u32_e32 v134, v134, v135
	v_lshl_add_u64 v[176:177], v[132:133], 0, v[0:1]
	v_mul_i32_i24_e32 v0, 0x1100, v134
	global_load_dwordx4 v[132:135], v181, s[36:37] offset:16
	global_load_dwordx4 v[216:219], v181, s[36:37] offset:48
	global_load_dwordx4 v[220:223], v181, s[36:37] offset:32
	v_cmp_gt_u32_e32 vcc, 2, v211
	v_sub_u32_e32 v0, v160, v0
	v_add_u32_e32 v211, 0xffffff00, v0
	v_lshlrev_b32_e32 v0, 4, v0
	v_and_or_b32 v0, v0, s3, v180
	v_lshlrev_b32_e32 v0, 3, v0
	v_readlane_b32 s2, v249, 16
	v_readlane_b32 s3, v249, 17
	s_waitcnt vmcnt(9)
	v_and_b32_e32 v229, 0xffff0000, v136
	v_lshlrev_b32_e32 v228, 16, v136
	v_and_b32_e32 v233, 0xffff0000, v139
	v_lshlrev_b32_e32 v232, 16, v139
	s_waitcnt vmcnt(8)
	v_mov_b32_e32 v139, v154
	v_mov_b32_e32 v154, v153
	v_and_b32_e32 v231, 0xffff0000, v137
	v_lshlrev_b32_e32 v230, 16, v137
	v_and_b32_e32 v137, 0xffff0000, v138
	v_lshlrev_b32_e32 v136, 16, v138
	v_mov_b32_e32 v138, v152
	s_waitcnt vmcnt(7)
	v_mov_b32_e32 v152, v148
	v_mov_b32_e32 v153, v150
	v_mov_b32_e32 v150, v149
	s_waitcnt vmcnt(6)
	v_mov_b32_e32 v148, v144
	v_mov_b32_e32 v149, v146
	v_mov_b32_e32 v146, v145
	s_waitcnt vmcnt(5)
	v_mov_b32_e32 v144, v140
	v_mov_b32_e32 v145, v142
	v_mov_b32_e32 v142, v141
	v_pk_mul_f32 v[140:141], v[154:155], v[228:229]
	v_pk_mul_f32 v[136:137], v[146:147], v[136:137]
	v_cndmask_b32_e64 v141, v141, -v141, vcc
	v_cndmask_b32_e64 v140, v140, -v140, vcc
	v_cndmask_b32_e64 v137, v137, -v137, vcc
	v_cndmask_b32_e64 v136, v136, -v136, vcc
	v_pk_fma_f32 v[2:3], v[138:139], v[2:3], v[140:141]
	v_pk_fma_f32 v[148:149], v[148:149], v[224:225], v[136:137]
	v_bfe_u32 v136, v2, 16, 1
	v_add3_u32 v228, v2, v136, s33
	v_ashrrev_i32_e32 v2, 2, v211
	v_pk_mul_f32 v[150:151], v[150:151], v[230:231]
	v_and_or_b32 v140, v2, -16, v180
	v_pk_mul_f32 v[142:143], v[142:143], v[232:233]
	v_cndmask_b32_e64 v147, v151, -v151, vcc
	v_cndmask_b32_e64 v146, v150, -v150, vcc
	v_ashrrev_i32_e32 v141, 31, v140
	v_cndmask_b32_e64 v143, v143, -v143, vcc
	v_cndmask_b32_e64 v142, v142, -v142, vcc
	v_pk_fma_f32 v[150:151], v[152:153], v[178:179], v[146:147]
	v_lshl_add_u64 v[154:155], v[140:141], 3, s[36:37]
	v_pk_fma_f32 v[152:153], v[144:145], v[226:227], v[142:143]
	v_bfe_u32 v181, v149, 16, 1
	v_bfe_u32 v224, v148, 16, 1
	v_bfe_u32 v225, v151, 16, 1
	v_bfe_u32 v227, v3, 16, 1
	global_load_dwordx4 v[136:139], v[176:177], off offset:256
	global_load_dwordx4 v[140:143], v[154:155], off offset:16
	global_load_dwordx4 v[144:147], v[154:155], off
	v_add3_u32 v211, v3, v227, s33
	v_add3_u32 v225, v151, v225, s33
	v_add3_u32 v224, v148, v224, s33
	v_add3_u32 v227, v149, v181, s33
	s_waitcnt vmcnt(7)
	v_and_b32_e32 v149, 0xffff0000, v156
	v_lshlrev_b32_e32 v148, 16, v156
	s_waitcnt vmcnt(6)
	v_mov_b32_e32 v151, v214
	v_mov_b32_e32 v214, v213
	v_bfe_u32 v226, v150, 16, 1
	v_pk_mul_f32 v[148:149], v[214:215], v[148:149]
	v_bfe_u32 v178, v153, 16, 1
	v_bfe_u32 v179, v152, 16, 1
	v_add3_u32 v226, v150, v226, s33
	v_and_b32_e32 v3, 0xffff0000, v128
	v_lshlrev_b32_e32 v2, 16, v128
	v_mov_b32_e32 v150, v212
	v_cndmask_b32_e64 v149, v149, -v149, vcc
	v_cndmask_b32_e64 v148, v148, -v148, vcc
	v_add3_u32 v229, v152, v179, s33
	v_add3_u32 v230, v153, v178, s33
	v_pk_fma_f32 v[2:3], v[150:151], v[2:3], v[148:149]
	global_load_dwordx4 v[148:151], v[154:155], off offset:48
	s_nop 0
	global_load_dwordx4 v[152:155], v[154:155], off offset:32
	v_and_b32_e32 v179, 0xffff0000, v129
	v_lshlrev_b32_e32 v178, 16, v129
	v_and_b32_e32 v129, 0xffff0000, v157
	v_lshlrev_b32_e32 v128, 16, v157
	s_waitcnt vmcnt(7)
	v_mov_b32_e32 v157, v134
	v_mov_b32_e32 v134, v133
	v_mov_b32_e32 v156, v132
	v_pk_mul_f32 v[128:129], v[134:135], v[128:129]
	v_and_b32_e32 v133, 0xffff0000, v158
	v_lshlrev_b32_e32 v132, 16, v158
	s_waitcnt vmcnt(5)
; DEVI float bfs(short h) { return __uint_as_float(((unsigned)(u16)h) << 16); }
; template <int DQK, int QT, bool NA> ...
;     ...
;         for (int hf = 0; hf < 2; ++hf) {
;           bf16x8 own = qf[qt][KS - 2 + hf];
;           bf16x8 par = *(const bf16x8*)(qp + 128 + hf * 32 + (quad ^ 2) * 8);
;           int pp = hf ? (tq & 63) : (tq >> 6);
;           bf16x8 ro;
; #pragma unroll
;           for (int e = 0; e < 8; ++e) {
;             float2 cs = rt[pp * 16 + (quad & 1) * 8 + e];
;             float ov = bfs(own[e]), pv = bfs(par[e]);
;             float r = (quad < 2) ? ov * cs.x - pv * cs.y : ov * cs.x + pv * cs.y;
;             ro[e] = (short)f2bf(r);
;           }
;           qf[qt][KS - 2 + hf] = ro;
;         }
;       }
;     }
;     for (int ti = 4; ti < ntile; ++ti) tile_iter(ti);
	v_mov_b32_e32 v135, v222
	v_mov_b32_e32 v222, v221
	v_cndmask_b32_e64 v129, v129, -v129, vcc
	v_cndmask_b32_e64 v128, v128, -v128, vcc
	v_pk_mul_f32 v[132:133], v[222:223], v[132:133]
	v_pk_fma_f32 v[178:179], v[156:157], v[178:179], v[128:129]
	v_and_b32_e32 v129, 0xffff0000, v130
	v_lshlrev_b32_e32 v128, 16, v130
	v_mov_b32_e32 v134, v220
	v_cndmask_b32_e64 v133, v133, -v133, vcc
	v_cndmask_b32_e64 v132, v132, -v132, vcc
	v_pk_fma_f32 v[212:213], v[134:135], v[128:129], v[132:133]
	v_and_b32_e32 v129, 0xffff0000, v131
	v_lshlrev_b32_e32 v128, 16, v131
	v_and_b32_e32 v131, 0xffff0000, v159
	v_lshlrev_b32_e32 v130, 16, v159
	v_mov_b32_e32 v133, v218
	v_mov_b32_e32 v218, v217
	v_pk_mul_f32 v[130:131], v[218:219], v[130:131]
	v_mov_b32_e32 v132, v216
	v_cndmask_b32_e64 v131, v131, -v131, vcc
	v_cndmask_b32_e64 v130, v130, -v130, vcc
	v_pk_fma_f32 v[214:215], v[132:133], v[128:129], v[130:131]
	global_load_dwordx4 v[128:131], v[176:177], off offset:320
	global_load_dwordx4 v[132:135], v0, s[36:37] offset:16
	global_load_dwordx4 v[156:159], v0, s[36:37]
	v_bfe_u32 v181, v215, 16, 1
	v_bfe_u32 v216, v214, 16, 1
	v_bfe_u32 v217, v213, 16, 1
	v_bfe_u32 v176, v212, 16, 1
	v_bfe_u32 v177, v179, 16, 1
	v_bfe_u32 v180, v178, 16, 1
	v_add3_u32 v220, v178, v180, s33
	v_add3_u32 v221, v179, v177, s33
	v_add3_u32 v222, v212, v176, s33
	v_add3_u32 v223, v213, v217, s33
	v_add3_u32 v231, v214, v216, s33
	v_add3_u32 v232, v215, v181, s33
	global_load_dwordx4 v[176:179], v0, s[36:37] offset:48
	global_load_dwordx4 v[212:215], v0, s[36:37] offset:32
	v_bfe_u32 v218, v3, 16, 1
	v_bfe_u32 v219, v2, 16, 1
	v_add3_u32 v219, v2, v219, s33
	v_add3_u32 v218, v3, v218, s33
	v_and_b32_e32 v3, 0xffff0000, v124
	v_lshlrev_b32_e32 v2, 16, v124
	s_waitcnt vmcnt(9)
	v_and_b32_e32 v181, 0xffff0000, v136
	v_lshlrev_b32_e32 v180, 16, v136
	s_waitcnt vmcnt(7)
	v_mov_b32_e32 v217, v146
	v_mov_b32_e32 v146, v145
	v_mov_b32_e32 v216, v144
	v_pk_mul_f32 v[144:145], v[146:147], v[180:181]
	v_lshlrev_b32_e32 v124, 16, v137
	v_cndmask_b32_e64 v145, v145, -v145, vcc
	v_cndmask_b32_e64 v144, v144, -v144, vcc
	v_pk_fma_f32 v[2:3], v[216:217], v[2:3], v[144:145]
	v_and_b32_e32 v145, 0xffff0000, v125
	v_lshlrev_b32_e32 v144, 16, v125
	v_and_b32_e32 v125, 0xffff0000, v137
	v_mov_b32_e32 v137, v142
	v_mov_b32_e32 v142, v141
	v_mov_b32_e32 v136, v140
	v_pk_mul_f32 v[124:125], v[142:143], v[124:125]
	v_and_b32_e32 v141, 0xffff0000, v138
	v_lshlrev_b32_e32 v140, 16, v138
	v_cndmask_b32_e64 v125, v125, -v125, vcc
	v_cndmask_b32_e64 v124, v124, -v124, vcc
	v_pk_fma_f32 v[124:125], v[136:137], v[144:145], v[124:125]
	v_and_b32_e32 v137, 0xffff0000, v126
	s_waitcnt vmcnt(5)
	v_mov_b32_e32 v143, v154
	v_mov_b32_e32 v154, v153
	v_pk_mul_f32 v[140:141], v[154:155], v[140:141]
	v_lshlrev_b32_e32 v136, 16, v126
	v_mov_b32_e32 v142, v152
	v_cndmask_b32_e64 v141, v141, -v141, vcc
	v_cndmask_b32_e64 v140, v140, -v140, vcc
	v_pk_fma_f32 v[136:137], v[142:143], v[136:137], v[140:141]
	v_and_b32_e32 v141, 0xffff0000, v127
	v_lshlrev_b32_e32 v140, 16, v127
	v_and_b32_e32 v127, 0xffff0000, v139
	v_lshlrev_b32_e32 v126, 16, v139
	v_mov_b32_e32 v139, v150
	v_mov_b32_e32 v150, v149
	v_pk_mul_f32 v[126:127], v[150:151], v[126:127]
	v_mov_b32_e32 v138, v148
	v_cndmask_b32_e64 v127, v127, -v127, vcc
	v_cndmask_b32_e64 v126, v126, -v126, vcc
	v_pk_fma_f32 v[126:127], v[138:139], v[140:141], v[126:127]
	v_bfe_u32 v141, v125, 16, 1
	v_bfe_u32 v0, v127, 16, 1
	v_bfe_u32 v142, v124, 16, 1
	v_add3_u32 v142, v124, v142, s33
	v_add3_u32 v141, v125, v141, s33
	v_add3_u32 v0, v127, v0, s33
	v_bfe_u32 v138, v126, 16, 1
	v_bfe_u32 v143, v3, 16, 1
	v_bfe_u32 v144, v2, 16, 1
	v_add3_u32 v144, v2, v144, s33
	v_add3_u32 v143, v3, v143, s33
	v_add3_u32 v138, v126, v138, s33
	v_and_b32_e32 v3, 0xffff0000, v120
	v_lshlrev_b32_e32 v2, 16, v120
	v_bfe_u32 v139, v137, 16, 1
	s_waitcnt vmcnt(4)
	v_and_b32_e32 v125, 0xffff0000, v128
	v_lshlrev_b32_e32 v124, 16, v128
	s_waitcnt vmcnt(2)
	v_mov_b32_e32 v127, v158
	v_mov_b32_e32 v158, v157
	v_pk_mul_f32 v[124:125], v[158:159], v[124:125]
	v_mov_b32_e32 v126, v156
	v_cndmask_b32_e64 v125, v125, -v125, vcc
	v_cndmask_b32_e64 v124, v124, -v124, vcc
	v_pk_fma_f32 v[2:3], v[126:127], v[2:3], v[124:125]
	v_and_b32_e32 v125, 0xffff0000, v121
	v_lshlrev_b32_e32 v124, 16, v121
	v_and_b32_e32 v121, 0xffff0000, v129
	v_lshlrev_b32_e32 v120, 16, v129
	v_mov_b32_e32 v127, v134
	v_mov_b32_e32 v134, v133
	v_pk_mul_f32 v[120:121], v[134:135], v[120:121]
	v_mov_b32_e32 v126, v132
	v_cndmask_b32_e64 v121, v121, -v121, vcc
	v_cndmask_b32_e64 v120, v120, -v120, vcc
	v_pk_fma_f32 v[120:121], v[126:127], v[124:125], v[120:121]
	v_and_b32_e32 v127, 0xffff0000, v130
	v_lshlrev_b32_e32 v126, 16, v130
	s_waitcnt vmcnt(0)
	v_mov_b32_e32 v129, v214
	v_mov_b32_e32 v214, v213
	v_pk_mul_f32 v[126:127], v[214:215], v[126:127]
	v_and_b32_e32 v125, 0xffff0000, v122
	v_lshlrev_b32_e32 v124, 16, v122
	v_mov_b32_e32 v128, v212
	v_cndmask_b32_e64 v127, v127, -v127, vcc
	v_cndmask_b32_e64 v126, v126, -v126, vcc
	v_pk_fma_f32 v[124:125], v[128:129], v[124:125], v[126:127]
	v_and_b32_e32 v127, 0xffff0000, v123
	v_lshlrev_b32_e32 v126, 16, v123
	v_and_b32_e32 v123, 0xffff0000, v131
	v_lshlrev_b32_e32 v122, 16, v131
	v_mov_b32_e32 v129, v178
	v_mov_b32_e32 v178, v177
	v_pk_mul_f32 v[122:123], v[178:179], v[122:123]
	v_mov_b32_e32 v128, v176
	v_cndmask_b32_e64 v123, v123, -v123, vcc
	v_cndmask_b32_e64 v122, v122, -v122, vcc
	v_pk_fma_f32 v[122:123], v[128:129], v[126:127], v[122:123]
	v_bfe_u32 v128, v125, 16, 1
	v_bfe_u32 v126, v123, 16, 1
	v_bfe_u32 v127, v122, 16, 1
	v_bfe_u32 v129, v124, 16, 1
	v_bfe_u32 v132, v3, 16, 1
	v_bfe_u32 v133, v2, 16, 1
	v_add3_u32 v2, v2, v133, s33
	v_add3_u32 v3, v3, v132, s33
	v_add3_u32 v124, v124, v129, s33
	v_add3_u32 v125, v125, v128, s33
	v_add3_u32 v127, v122, v127, s33
	v_add3_u32 v126, v123, v126, s33
	v_bfe_u32 v140, v136, 16, 1
	v_bfe_u32 v130, v121, 16, 1
	v_bfe_u32 v131, v120, 16, 1
	v_perm_b32 v127, v126, v127, s27
	v_perm_b32 v126, v125, v124, s27
	v_perm_b32 v124, v3, v2, s27
	v_lshl_add_u64 v[2:3], s[2:3], 0, v[164:165]
	v_lshl_add_u64 v[152:153], s[2:3], 0, v[166:167]
	v_lshl_add_u64 v[154:155], s[2:3], 0, v[168:169]
	v_readlane_b32 s2, v249, 18
	v_add3_u32 v136, v136, v140, s33
	v_add3_u32 v137, v137, v139, s33
	v_add3_u32 v139, v120, v131, s33
	v_add3_u32 v140, v121, v130, s33
	v_readlane_b32 s3, v249, 19
	v_perm_b32 v131, v230, v229, s27
	v_perm_b32 v130, v227, v224, s27
	v_perm_b32 v129, v225, v226, s27
	v_perm_b32 v128, v211, v228, s27
	v_perm_b32 v135, v0, v138, s27
	v_perm_b32 v134, v137, v136, s27
	v_perm_b32 v133, v141, v142, s27
	v_perm_b32 v132, v143, v144, s27
	v_perm_b32 v123, v232, v231, s27
	v_perm_b32 v122, v223, v222, s27
	v_perm_b32 v121, v221, v220, s27
	v_perm_b32 v120, v218, v219, s27
	v_perm_b32 v125, v140, v139, s27
	v_lshl_add_u64 v[156:157], s[2:3], 0, v[172:173]
	v_lshl_add_u64 v[158:159], s[2:3], 0, v[174:175]
	s_mov_b32 s2, 62
	v_readfirstlane_b32 s3, v171
	s_nop 3
	s_cmp_lt_u32 s3, 0x100
	s_cbranch_scc1 .Lmla_prio_skip
	s_setprio 1
; #define LDS_BAR() do { asm volatile("s_waitcnt lgkmcnt(0)" ::: "memory"); __builtin_amdgcn_s_barrier(); asm volatile("" ::: "memory"); } while (0)
; template <int DQK, int QT, bool NA> ...
;     ...
;     f32x4 s[4][QT];
;     if (active) {
; #pragma unroll
;       for (int kt = 0; kt < 4; ++kt)
; #pragma unroll
;         for (int qt = 0; qt < QT; ++qt) s[kt][qt] = f32x4{0.f, 0.f, 0.f, 0.f};
; #pragma unroll
;       for (int ks = 0; ks < KS; ++ks) {
;         bf16x8 a[4];
; #pragma unroll
;         for (int kt = 0; kt < 4; ++kt) a[kt] = *(const bf16x8*)(Ks + (kt * 16 + l15) * KSTR + ks * 32 + quad * 8);
; #pragma unroll
;         for (int qt = 0; qt < QT; ++qt) {
;           bf16x8 q = qf[qt][ks];
; #pragma unroll
;           for (int kt = 0; kt < 4; ++kt) s[kt][qt] = __builtin_amdgcn_mfma_f32_16x16x32_bf16(a[kt], q, s[kt][qt], 0, 0, 0);
;         }
;       }
;     }
;     LDS_BAR();
.Lmla_prio_skip:
.LBB0_787:
	ds_read_b128 v[136:139], v183
	ds_read_b128 v[140:143], v183 offset:6400
	ds_read_b128 v[144:147], v183 offset:12800
	ds_read_b128 v[148:151], v183 offset:19200
	ds_read_b128 v[216:219], v183 offset:64
	ds_read_b128 v[220:223], v183 offset:6464
	ds_read_b128 v[224:227], v183 offset:12864
	ds_read_b128 v[228:231], v183 offset:19264
	s_waitcnt lgkmcnt(7)
	v_mfma_f32_16x16x32_bf16 v[164:167], v[136:139], v[28:31], 0
	v_mov_b32_e32 v0, v207
	s_waitcnt lgkmcnt(6)
	v_mfma_f32_16x16x32_bf16 v[172:175], v[140:143], v[28:31], 0
	s_waitcnt lgkmcnt(5)
	v_mfma_f32_16x16x32_bf16 v[176:179], v[144:147], v[28:31], 0
	s_waitcnt lgkmcnt(4)
	v_mfma_f32_16x16x32_bf16 v[212:215], v[148:151], v[28:31], 0
	v_mfma_f32_16x16x32_bf16 v[136:139], v[136:139], v[32:35], 0
	v_mfma_f32_16x16x32_bf16 v[140:143], v[140:143], v[32:35], 0
	v_mfma_f32_16x16x32_bf16 v[144:147], v[144:147], v[32:35], 0
	v_mfma_f32_16x16x32_bf16 v[148:151], v[148:151], v[32:35], 0
	s_waitcnt lgkmcnt(3)
	v_mfma_f32_16x16x32_bf16 v[164:167], v[216:219], v[20:23], v[164:167]
	s_waitcnt lgkmcnt(2)
	v_mfma_f32_16x16x32_bf16 v[172:175], v[220:223], v[20:23], v[172:175]
	s_waitcnt lgkmcnt(1)
	v_mfma_f32_16x16x32_bf16 v[176:179], v[224:227], v[20:23], v[176:179]
	s_waitcnt lgkmcnt(0)
	v_mfma_f32_16x16x32_bf16 v[212:215], v[228:231], v[20:23], v[212:215]
	v_mfma_f32_16x16x32_bf16 v[136:139], v[216:219], v[24:27], v[136:139]
	v_mfma_f32_16x16x32_bf16 v[140:143], v[220:223], v[24:27], v[140:143]
	v_mfma_f32_16x16x32_bf16 v[144:147], v[224:227], v[24:27], v[144:147]
	v_mfma_f32_16x16x32_bf16 v[148:151], v[228:231], v[24:27], v[148:151]
	ds_read_b128 v[216:219], v183 offset:128
	ds_read_b128 v[220:223], v183 offset:6528
	ds_read_b128 v[224:227], v183 offset:12928
	ds_read_b128 v[228:231], v183 offset:19328
	s_waitcnt lgkmcnt(3)
	v_mfma_f32_16x16x32_bf16 v[164:167], v[216:219], v[12:15], v[164:167]
	s_waitcnt lgkmcnt(2)
	v_mfma_f32_16x16x32_bf16 v[172:175], v[220:223], v[12:15], v[172:175]
	s_waitcnt lgkmcnt(1)
	v_mfma_f32_16x16x32_bf16 v[176:179], v[224:227], v[12:15], v[176:179]
	s_waitcnt lgkmcnt(0)
	v_mfma_f32_16x16x32_bf16 v[212:215], v[228:231], v[12:15], v[212:215]
	v_mfma_f32_16x16x32_bf16 v[136:139], v[216:219], v[16:19], v[136:139]
	v_mfma_f32_16x16x32_bf16 v[140:143], v[220:223], v[16:19], v[140:143]
	v_mfma_f32_16x16x32_bf16 v[144:147], v[224:227], v[16:19], v[144:147]
	v_mfma_f32_16x16x32_bf16 v[148:151], v[228:231], v[16:19], v[148:151]
	ds_read_b128 v[216:219], v183 offset:192
	ds_read_b128 v[220:223], v183 offset:6592
	ds_read_b128 v[224:227], v183 offset:12992
	ds_read_b128 v[228:231], v183 offset:19392
	s_waitcnt lgkmcnt(3)
	v_mfma_f32_16x16x32_bf16 v[164:167], v[216:219], v[4:7], v[164:167]
	s_waitcnt lgkmcnt(2)
	v_mfma_f32_16x16x32_bf16 v[172:175], v[220:223], v[4:7], v[172:175]
	s_waitcnt lgkmcnt(1)
	v_mfma_f32_16x16x32_bf16 v[176:179], v[224:227], v[4:7], v[176:179]
	s_waitcnt lgkmcnt(0)
	v_mfma_f32_16x16x32_bf16 v[212:215], v[228:231], v[4:7], v[212:215]
	v_mfma_f32_16x16x32_bf16 v[136:139], v[216:219], v[8:11], v[136:139]
	v_mfma_f32_16x16x32_bf16 v[140:143], v[220:223], v[8:11], v[140:143]
	v_mfma_f32_16x16x32_bf16 v[144:147], v[224:227], v[8:11], v[144:147]
	v_mfma_f32_16x16x32_bf16 v[148:151], v[228:231], v[8:11], v[148:151]
	ds_read_b128 v[216:219], v183 offset:256
	ds_read_b128 v[220:223], v183 offset:6656
	ds_read_b128 v[224:227], v183 offset:13056
	ds_read_b128 v[228:231], v183 offset:19456
	s_waitcnt lgkmcnt(3)
	v_mfma_f32_16x16x32_bf16 v[164:167], v[216:219], v[128:131], v[164:167]
	s_waitcnt lgkmcnt(2)
	v_mfma_f32_16x16x32_bf16 v[172:175], v[220:223], v[128:131], v[172:175]
	s_waitcnt lgkmcnt(1)
	v_mfma_f32_16x16x32_bf16 v[176:179], v[224:227], v[128:131], v[176:179]
	s_waitcnt lgkmcnt(0)
	v_mfma_f32_16x16x32_bf16 v[212:215], v[228:231], v[128:131], v[212:215]
	v_mfma_f32_16x16x32_bf16 v[136:139], v[216:219], v[132:135], v[136:139]
	v_mfma_f32_16x16x32_bf16 v[140:143], v[220:223], v[132:135], v[140:143]
	v_mfma_f32_16x16x32_bf16 v[216:219], v[224:227], v[132:135], v[144:147]
	v_mfma_f32_16x16x32_bf16 v[220:223], v[228:231], v[132:135], v[148:151]
	s_nop 1
	ds_read_b128 v[144:147], v183 offset:320
	ds_read_b128 v[224:227], v183 offset:6720
	ds_read_b128 v[228:231], v183 offset:13120
	ds_read_b128 v[232:235], v183 offset:19520
	s_waitcnt lgkmcnt(0)
	s_barrier
; #define SHX(v, m) __int_as_float(__builtin_amdgcn_ds_bpermute(((LANE ^ (m)) << 2), __float_as_int(v)))
; #define LDS_BAR() do { asm volatile("s_waitcnt lgkmcnt(0)" ::: "memory"); __builtin_amdgcn_s_barrier(); asm volatile("" ::: "memory"); } while (0)
; template <int DQK, int QT, bool NA> ...
;     ...
;     LDS_BAR();
;     if (ti + 1 < ntile) sstoreK();
;     if (ti + 2 < ntile) gloadK(ti + 2);
;     if (active) {
;       bf16x8 pf[QT][2];
; #pragma unroll
;       for (int qt = 0; qt < QT; ++qt) {
;         float mx = -1e30f;
; #pragma unroll
;         for (int kt = 0; kt < 4; ++kt)
; #pragma unroll
;           for (int j = 0; j < 4; ++j) {
;             float v = s[kt][qt][j] * scale2;
;             if (NA && !isctx) {
;               int ck = kt * 16 + quad * 4 + j;
;               bool valid = (ck >= na_cs) && (ck < na_cs + 16);
;               int bidx = (kr - na_rq + 7) * 31 + min(max(ck - na_cq + 15, 0), 30);
;               v = valid ? v + rpb[bidx] * 1.4426950408889634f : -1e30f;
;             }
;             s[kt][qt][j] = v;
;             mx = fmaxf(mx, v);
;           }
;         mx = fmaxf(mx, SHX(mx, 16));
;         mx = fmaxf(mx, SHX(mx, 32));
;         float mnew = fmaxf(mrun[qt], mx);
;         float alpha = __builtin_amdgcn_exp2f(mrun[qt] - mnew);
;         mrun[qt] = mnew;
;         float ls = 0.f;
; #pragma unroll
;         for (int kt = 0; kt < 4; ++kt)
; #pragma unroll
;           for (int j = 0; j < 4; ++j) {
;             float pv = __builtin_amdgcn_exp2f(s[kt][qt][j] - mnew);
;             ls += pv;
;             s[kt][qt][j] = pv;
;           }
;         lrun[qt] = lrun[qt] * alpha + ls;
;         if (__builtin_amdgcn_ballot_w64(alpha != 1.f)) {
; #pragma unroll
;           for (int dt = 0; dt < 8; ++dt)
; #pragma unroll
;             for (int j = 0; j < 4; ++j) o[dt][qt][j] *= alpha;
;         }
	s_waitcnt vmcnt(4)
	ds_write_b128 v204, v[108:111]
	s_waitcnt vmcnt(3)
	ds_write_b128 v205, v[112:115]
	s_waitcnt vmcnt(2)
	ds_write_b128 v206, v[116:119]
	v_lshl_add_u64 v[108:109], v[2:3], 0, s[28:29]
	v_lshl_add_u64 v[112:113], v[152:153], 0, s[28:29]
	v_lshl_add_u64 v[116:117], v[154:155], 0, s[28:29]
	global_load_dwordx4 v[108:111], v[108:109], off
	s_waitcnt lgkmcnt(6)
	v_mfma_f32_16x16x32_bf16 v[166:169], v[144:147], v[120:123], v[164:167]
	global_load_dwordx4 v[112:115], v[112:113], off
	s_nop 0
	global_load_dwordx4 v[116:119], v[116:117], off
	s_waitcnt lgkmcnt(5)
	v_mfma_f32_16x16x32_bf16 v[172:175], v[224:227], v[120:123], v[172:175]
	s_waitcnt lgkmcnt(4)
	v_mfma_f32_16x16x32_bf16 v[176:179], v[228:231], v[120:123], v[176:179]
	s_nop 0
	v_mul_f32_e32 v165, 0x3dd53b94, v166
	v_mul_f32_e32 v164, 0x3dd53b94, v167
	v_max3_f32 v166, v165, s94, v164
	v_mul_f32_e32 v168, 0x3dd53b94, v168
	v_mul_f32_e32 v167, 0x3dd53b94, v169
	s_waitcnt lgkmcnt(3)
	v_mfma_f32_16x16x32_bf16 v[212:215], v[232:235], v[120:123], v[212:215]
	v_max3_f32 v166, v166, v168, v167
	v_mul_f32_e32 v172, 0x3dd53b94, v172
	v_mul_f32_e32 v169, 0x3dd53b94, v173
	v_max3_f32 v166, v166, v172, v169
	v_mul_f32_e32 v174, 0x3dd53b94, v174
	v_mul_f32_e32 v173, 0x3dd53b94, v175
	v_max3_f32 v166, v166, v174, v173
	v_mul_f32_e32 v176, 0x3dd53b94, v176
	v_mul_f32_e32 v175, 0x3dd53b94, v177
	v_max3_f32 v166, v166, v176, v175
	v_mul_f32_e32 v178, 0x3dd53b94, v178
	v_mul_f32_e32 v177, 0x3dd53b94, v179
	v_max3_f32 v166, v166, v178, v177
	v_mul_f32_e32 v180, 0x3dd53b94, v212
	v_mul_f32_e32 v179, 0x3dd53b94, v213
	v_max3_f32 v166, v166, v180, v179
	v_mul_f32_e32 v211, 0x3dd53b94, v214
	v_mul_f32_e32 v181, 0x3dd53b94, v215
	v_max3_f32 v166, v166, v211, v181
	ds_bpermute_b32 v207, v161, v166
	v_mfma_f32_16x16x32_bf16 v[148:151], v[144:147], v[124:127], v[136:139]
	s_waitcnt lgkmcnt(0)
	v_max_f32_e32 v207, v207, v207
	v_max_f32_e32 v166, v166, v207
	ds_bpermute_b32 v207, v163, v166
	v_mfma_f32_16x16x32_bf16 v[144:147], v[224:227], v[124:127], v[140:143]
	s_waitcnt lgkmcnt(0)
	v_max3_f32 v207, v0, v166, v207
	v_sub_f32_e32 v0, v0, v207
	v_exp_f32_e32 v0, v0
	v_mfma_f32_16x16x32_bf16 v[140:143], v[228:231], v[124:127], v[216:219]
	v_cmp_neq_f32_e32 vcc, 1.0, v0
	v_mfma_f32_16x16x32_bf16 v[136:139], v[232:235], v[124:127], v[220:223]
	s_cbranch_vccz .LBB0_789
	v_pk_mul_f32 v[106:107], v[106:107], v[0:1] op_sel_hi:[1,0]
	v_pk_mul_f32 v[104:105], v[104:105], v[0:1] op_sel_hi:[1,0]
	v_pk_mul_f32 v[98:99], v[98:99], v[0:1] op_sel_hi:[1,0]
	v_pk_mul_f32 v[96:97], v[96:97], v[0:1] op_sel_hi:[1,0]
	v_pk_mul_f32 v[90:91], v[90:91], v[0:1] op_sel_hi:[1,0]
	v_pk_mul_f32 v[88:89], v[88:89], v[0:1] op_sel_hi:[1,0]
	v_pk_mul_f32 v[82:83], v[82:83], v[0:1] op_sel_hi:[1,0]
	v_pk_mul_f32 v[80:81], v[80:81], v[0:1] op_sel_hi:[1,0]
	v_pk_mul_f32 v[74:75], v[74:75], v[0:1] op_sel_hi:[1,0]
	v_pk_mul_f32 v[72:73], v[72:73], v[0:1] op_sel_hi:[1,0]
	v_pk_mul_f32 v[66:67], v[66:67], v[0:1] op_sel_hi:[1,0]
	v_pk_mul_f32 v[64:65], v[64:65], v[0:1] op_sel_hi:[1,0]
	v_pk_mul_f32 v[58:59], v[58:59], v[0:1] op_sel_hi:[1,0]
	v_pk_mul_f32 v[56:57], v[56:57], v[0:1] op_sel_hi:[1,0]
	v_pk_mul_f32 v[50:51], v[50:51], v[0:1] op_sel_hi:[1,0]
	v_pk_mul_f32 v[48:49], v[48:49], v[0:1] op_sel_hi:[1,0]

; #define LDS_BAR() do { asm volatile("s_waitcnt lgkmcnt(0)" ::: "memory"); __builtin_amdgcn_s_barrier(); asm volatile("" ::: "memory"); } while (0)
; template <int DQK, int QT, bool NA> ...
;     ...
;     f32x4 s[4][QT];
;     if (active) {
; #pragma unroll
;       for (int kt = 0; kt < 4; ++kt)
; #pragma unroll
;         for (int qt = 0; qt < QT; ++qt) s[kt][qt] = f32x4{0.f, 0.f, 0.f, 0.f};
; #pragma unroll
;       for (int ks = 0; ks < KS; ++ks) {
;         bf16x8 a[4];
; #pragma unroll
;         for (int kt = 0; kt < 4; ++kt) a[kt] = *(const bf16x8*)(Ks + (kt * 16 + l15) * KSTR + ks * 32 + quad * 8);
; #pragma unroll
;         for (int qt = 0; qt < QT; ++qt) {
;           bf16x8 q = qf[qt][ks];
; #pragma unroll
;           for (int kt = 0; kt < 4; ++kt) s[kt][qt] = __builtin_amdgcn_mfma_f32_16x16x32_bf16(a[kt], q, s[kt][qt], 0, 0, 0);
;         }
;       }
;     }
;     LDS_BAR();
.LBB0_793:
	s_setprio 0
	ds_read_b128 v[136:139], v183
	ds_read_b128 v[140:143], v183 offset:6400
	ds_read_b128 v[144:147], v183 offset:12800
	ds_read_b128 v[148:151], v183 offset:19200
	ds_read_b128 v[208:211], v183 offset:64
	ds_read_b128 v[212:215], v183 offset:6464
	ds_read_b128 v[216:219], v183 offset:12864
	ds_read_b128 v[220:223], v183 offset:19264
	s_waitcnt lgkmcnt(7)
	v_mfma_f32_16x16x32_bf16 v[152:155], v[136:139], v[28:31], 0
	s_waitcnt lgkmcnt(6)
	v_mfma_f32_16x16x32_bf16 v[156:159], v[140:143], v[28:31], 0
	s_waitcnt lgkmcnt(5)
	v_mfma_f32_16x16x32_bf16 v[172:175], v[144:147], v[28:31], 0
	s_waitcnt lgkmcnt(4)
	v_mfma_f32_16x16x32_bf16 v[176:179], v[148:151], v[28:31], 0
	v_mfma_f32_16x16x32_bf16 v[136:139], v[136:139], v[32:35], 0
	v_mfma_f32_16x16x32_bf16 v[140:143], v[140:143], v[32:35], 0
	v_mfma_f32_16x16x32_bf16 v[144:147], v[144:147], v[32:35], 0
	v_mfma_f32_16x16x32_bf16 v[148:151], v[148:151], v[32:35], 0
	s_waitcnt lgkmcnt(3)
	v_mfma_f32_16x16x32_bf16 v[152:155], v[208:211], v[20:23], v[152:155]
	s_waitcnt lgkmcnt(2)
	v_mfma_f32_16x16x32_bf16 v[156:159], v[212:215], v[20:23], v[156:159]
	s_waitcnt lgkmcnt(1)
	v_mfma_f32_16x16x32_bf16 v[172:175], v[216:219], v[20:23], v[172:175]
	s_waitcnt lgkmcnt(0)
	v_mfma_f32_16x16x32_bf16 v[176:179], v[220:223], v[20:23], v[176:179]
	v_mfma_f32_16x16x32_bf16 v[136:139], v[208:211], v[24:27], v[136:139]
	v_mfma_f32_16x16x32_bf16 v[140:143], v[212:215], v[24:27], v[140:143]
	v_mfma_f32_16x16x32_bf16 v[144:147], v[216:219], v[24:27], v[144:147]
	v_mfma_f32_16x16x32_bf16 v[148:151], v[220:223], v[24:27], v[148:151]
	ds_read_b128 v[208:211], v183 offset:128
	ds_read_b128 v[212:215], v183 offset:6528
	ds_read_b128 v[216:219], v183 offset:12928
	ds_read_b128 v[220:223], v183 offset:19328
	s_waitcnt lgkmcnt(3)
	v_mfma_f32_16x16x32_bf16 v[152:155], v[208:211], v[12:15], v[152:155]
	s_waitcnt lgkmcnt(2)
	v_mfma_f32_16x16x32_bf16 v[156:159], v[212:215], v[12:15], v[156:159]
	s_waitcnt lgkmcnt(1)
	v_mfma_f32_16x16x32_bf16 v[172:175], v[216:219], v[12:15], v[172:175]
	s_waitcnt lgkmcnt(0)
	v_mfma_f32_16x16x32_bf16 v[176:179], v[220:223], v[12:15], v[176:179]
	v_mfma_f32_16x16x32_bf16 v[136:139], v[208:211], v[16:19], v[136:139]
	v_mfma_f32_16x16x32_bf16 v[140:143], v[212:215], v[16:19], v[140:143]
	v_mfma_f32_16x16x32_bf16 v[144:147], v[216:219], v[16:19], v[144:147]
	v_mfma_f32_16x16x32_bf16 v[148:151], v[220:223], v[16:19], v[148:151]
	ds_read_b128 v[208:211], v183 offset:192
	ds_read_b128 v[212:215], v183 offset:6592
	ds_read_b128 v[216:219], v183 offset:12992
	ds_read_b128 v[220:223], v183 offset:19392
	s_waitcnt lgkmcnt(3)
	v_mfma_f32_16x16x32_bf16 v[152:155], v[208:211], v[4:7], v[152:155]
	s_waitcnt lgkmcnt(2)
	v_mfma_f32_16x16x32_bf16 v[156:159], v[212:215], v[4:7], v[156:159]
	s_waitcnt lgkmcnt(1)
	v_mfma_f32_16x16x32_bf16 v[172:175], v[216:219], v[4:7], v[172:175]
	s_waitcnt lgkmcnt(0)
	v_mfma_f32_16x16x32_bf16 v[176:179], v[220:223], v[4:7], v[176:179]
	v_mfma_f32_16x16x32_bf16 v[136:139], v[208:211], v[8:11], v[136:139]
	v_mfma_f32_16x16x32_bf16 v[140:143], v[212:215], v[8:11], v[140:143]
	v_mfma_f32_16x16x32_bf16 v[144:147], v[216:219], v[8:11], v[144:147]
	v_mfma_f32_16x16x32_bf16 v[148:151], v[220:223], v[8:11], v[148:151]
	ds_read_b128 v[208:211], v183 offset:256
	ds_read_b128 v[212:215], v183 offset:6656
	ds_read_b128 v[216:219], v183 offset:13056
	ds_read_b128 v[220:223], v183 offset:19456
	s_waitcnt lgkmcnt(3)
	v_mfma_f32_16x16x32_bf16 v[152:155], v[208:211], v[128:131], v[152:155]
	s_waitcnt lgkmcnt(2)
	v_mfma_f32_16x16x32_bf16 v[156:159], v[212:215], v[128:131], v[156:159]
	s_waitcnt lgkmcnt(1)
	v_mfma_f32_16x16x32_bf16 v[172:175], v[216:219], v[128:131], v[172:175]
	s_waitcnt lgkmcnt(0)
	v_mfma_f32_16x16x32_bf16 v[176:179], v[220:223], v[128:131], v[176:179]
	v_mfma_f32_16x16x32_bf16 v[136:139], v[208:211], v[132:135], v[136:139]
	v_mfma_f32_16x16x32_bf16 v[140:143], v[212:215], v[132:135], v[140:143]
	v_mfma_f32_16x16x32_bf16 v[208:211], v[216:219], v[132:135], v[144:147]
	v_mfma_f32_16x16x32_bf16 v[212:215], v[220:223], v[132:135], v[148:151]
	s_nop 1
	ds_read_b128 v[144:147], v183 offset:320
	ds_read_b128 v[216:219], v183 offset:6720
	ds_read_b128 v[220:223], v183 offset:13120
	ds_read_b128 v[224:227], v183 offset:19520
	s_waitcnt lgkmcnt(0)
	s_barrier
; #define SHX(v, m) __int_as_float(__builtin_amdgcn_ds_bpermute(((LANE ^ (m)) << 2), __float_as_int(v)))
; #define LDS_BAR() do { asm volatile("s_waitcnt lgkmcnt(0)" ::: "memory"); __builtin_amdgcn_s_barrier(); asm volatile("" ::: "memory"); } while (0)
; template <int DQK, int QT, bool NA> ...
;     ...
;     LDS_BAR();
;     if (ti + 1 < ntile) sstoreK();
;     if (ti + 2 < ntile) gloadK(ti + 2);
;     if (active) {
;       bf16x8 pf[QT][2];
; #pragma unroll
;       for (int qt = 0; qt < QT; ++qt) {
;         float mx = -1e30f;
; #pragma unroll
;         for (int kt = 0; kt < 4; ++kt)
; #pragma unroll
;           for (int j = 0; j < 4; ++j) {
;             float v = s[kt][qt][j] * scale2;
;             if (NA && !isctx) {
;               int ck = kt * 16 + quad * 4 + j;
;               bool valid = (ck >= na_cs) && (ck < na_cs + 16);
;               int bidx = (kr - na_rq + 7) * 31 + min(max(ck - na_cq + 15, 0), 30);
;               v = valid ? v + rpb[bidx] * 1.4426950408889634f : -1e30f;
;             }
;             s[kt][qt][j] = v;
;             mx = fmaxf(mx, v);
;           }
;         mx = fmaxf(mx, SHX(mx, 16));
;         mx = fmaxf(mx, SHX(mx, 32));
;         float mnew = fmaxf(mrun[qt], mx);
;         float alpha = __builtin_amdgcn_exp2f(mrun[qt] - mnew);
;         mrun[qt] = mnew;
;         float ls = 0.f;
; #pragma unroll
;         for (int kt = 0; kt < 4; ++kt)
; #pragma unroll
;           for (int j = 0; j < 4; ++j) {
;             float pv = __builtin_amdgcn_exp2f(s[kt][qt][j] - mnew);
;             ls += pv;
;             s[kt][qt][j] = pv;
;           }
;         lrun[qt] = lrun[qt] * alpha + ls;
;         if (__builtin_amdgcn_ballot_w64(alpha != 1.f)) {
; #pragma unroll
;           for (int dt = 0; dt < 8; ++dt)
; #pragma unroll
;             for (int j = 0; j < 4; ++j) o[dt][qt][j] *= alpha;
;         }
	s_waitcnt lgkmcnt(3)
	v_mfma_f32_16x16x32_bf16 v[152:155], v[144:147], v[120:123], v[152:155]
	s_waitcnt vmcnt(4)
	ds_write_b128 v204, v[108:111]
	s_waitcnt vmcnt(3)
	ds_write_b128 v205, v[112:115]
	s_waitcnt vmcnt(2)
	ds_write_b128 v206, v[116:119]
	s_waitcnt lgkmcnt(5)
	v_mfma_f32_16x16x32_bf16 v[156:159], v[216:219], v[120:123], v[156:159]
	v_mul_f32_e32 v3, 0x3dd53b94, v152
	v_mul_f32_e32 v2, 0x3dd53b94, v153
	v_max3_f32 v0, v3, s94, v2
	s_waitcnt lgkmcnt(4)
	v_mfma_f32_16x16x32_bf16 v[172:175], v[220:223], v[120:123], v[172:175]
	v_mul_f32_e32 v109, 0x3dd53b94, v154
	v_mul_f32_e32 v108, 0x3dd53b94, v155
	v_max3_f32 v0, v0, v109, v108
	s_waitcnt lgkmcnt(3)
	v_mfma_f32_16x16x32_bf16 v[176:179], v[224:227], v[120:123], v[176:179]
	v_mul_f32_e32 v111, 0x3dd53b94, v156
	v_mul_f32_e32 v110, 0x3dd53b94, v157
	v_max3_f32 v0, v0, v111, v110
	v_mul_f32_e32 v113, 0x3dd53b94, v158
	v_mul_f32_e32 v112, 0x3dd53b94, v159
	v_max3_f32 v0, v0, v113, v112
	v_mul_f32_e32 v115, 0x3dd53b94, v172
	v_mul_f32_e32 v114, 0x3dd53b94, v173
	v_max3_f32 v0, v0, v115, v114
	v_mul_f32_e32 v117, 0x3dd53b94, v174
	v_mul_f32_e32 v116, 0x3dd53b94, v175
	v_max3_f32 v0, v0, v117, v116
	v_mul_f32_e32 v119, 0x3dd53b94, v176
	v_mul_f32_e32 v118, 0x3dd53b94, v177
	v_max3_f32 v0, v0, v119, v118
	v_mul_f32_e32 v155, 0x3dd53b94, v178
	v_mul_f32_e32 v156, 0x3dd53b94, v179
	v_max3_f32 v0, v0, v155, v156
	ds_bpermute_b32 v152, v161, v0
	v_mfma_f32_16x16x32_bf16 v[148:151], v[144:147], v[124:127], v[136:139]
	s_waitcnt lgkmcnt(0)
	v_max_f32_e32 v152, v152, v152
	v_max_f32_e32 v0, v0, v152
	ds_bpermute_b32 v152, v163, v0
	v_mfma_f32_16x16x32_bf16 v[144:147], v[216:219], v[124:127], v[140:143]
	s_waitcnt lgkmcnt(0)
	v_max3_f32 v157, v207, v0, v152
	v_sub_f32_e32 v0, v207, v157
	v_exp_f32_e32 v0, v0
	v_mfma_f32_16x16x32_bf16 v[140:143], v[220:223], v[124:127], v[208:211]
	v_cmp_neq_f32_e32 vcc, 1.0, v0
	v_mfma_f32_16x16x32_bf16 v[136:139], v[224:227], v[124:127], v[212:215]
	s_cbranch_vccz .LBB0_795
	v_pk_mul_f32 v[106:107], v[106:107], v[0:1] op_sel_hi:[1,0]
	v_pk_mul_f32 v[104:105], v[104:105], v[0:1] op_sel_hi:[1,0]
	v_pk_mul_f32 v[98:99], v[98:99], v[0:1] op_sel_hi:[1,0]
	v_pk_mul_f32 v[96:97], v[96:97], v[0:1] op_sel_hi:[1,0]
	v_pk_mul_f32 v[90:91], v[90:91], v[0:1] op_sel_hi:[1,0]
	v_pk_mul_f32 v[88:89], v[88:89], v[0:1] op_sel_hi:[1,0]
	v_pk_mul_f32 v[82:83], v[82:83], v[0:1] op_sel_hi:[1,0]
	v_pk_mul_f32 v[80:81], v[80:81], v[0:1] op_sel_hi:[1,0]
	v_pk_mul_f32 v[74:75], v[74:75], v[0:1] op_sel_hi:[1,0]
	v_pk_mul_f32 v[72:73], v[72:73], v[0:1] op_sel_hi:[1,0]
	v_pk_mul_f32 v[66:67], v[66:67], v[0:1] op_sel_hi:[1,0]
	v_pk_mul_f32 v[64:65], v[64:65], v[0:1] op_sel_hi:[1,0]
	v_pk_mul_f32 v[58:59], v[58:59], v[0:1] op_sel_hi:[1,0]
	v_pk_mul_f32 v[56:57], v[56:57], v[0:1] op_sel_hi:[1,0]
	v_pk_mul_f32 v[50:51], v[50:51], v[0:1] op_sel_hi:[1,0]
	v_pk_mul_f32 v[48:49], v[48:49], v[0:1] op_sel_hi:[1,0]
